# v33 plus 7.4 step b: GEMM K-loop mid-block setprio 0/1 flips and already-satisfied lgkmcnt waits removed
# speedup vs baseline: 1.0046x; 1.0046x over previous
.LBB0_252:
	ds_read_b128 v[156:159], v149
	ds_read_b128 v[160:163], v149 offset:1024
	ds_read_b128 v[164:167], v149 offset:2048
	ds_read_b128 v[168:171], v149 offset:3072
	ds_read_b128 v[172:175], v150
	ds_read_b128 v[176:179], v150 offset:1024
	ds_read_b128 v[180:183], v150 offset:2048
	ds_read_b128 v[184:187], v150 offset:3072
	s_add_u32 s26, s24, 0xfffc0080
	s_addc_u32 s27, s25, -1
	s_cmp_eq_u32 s57, 12
	s_cselect_b32 s29, s19, s27
	s_cselect_b32 s28, s53, s26
	s_cselect_b32 s27, s17, s56
	s_cselect_b32 s26, s54, s55
	v_lshl_add_u64 v[146:147], s[24:25], 0, v[138:139]
	s_add_i32 m0, s38, 0xc000
	ds_read_b128 v[188:191], v151
	ds_read_b128 v[192:195], v151 offset:1024
	ds_read_b128 v[196:199], v151 offset:2048
	ds_read_b128 v[200:203], v151 offset:3072
	ds_read_b128 v[204:207], v151 offset:4096
	ds_read_b128 v[208:211], v151 offset:5120
	ds_read_b128 v[212:215], v151 offset:6144
	ds_read_b128 v[216:219], v151 offset:7168
	global_load_lds_dwordx4 v[146:147], off
	v_lshl_add_u64 v[146:147], s[24:25], 0, v[140:141]
	s_add_i32 m0, s38, 0xe000
	s_nop 0
	global_load_lds_dwordx4 v[146:147], off
	s_waitcnt vmcnt(8)
	s_waitcnt lgkmcnt(0)
	s_barrier
	s_setprio 1
	v_mfma_f32_16x16x32_bf16 v[122:125], v[156:159], v[188:191], v[122:125]
	v_mfma_f32_16x16x32_bf16 v[114:117], v[164:167], v[188:191], v[114:117]
	v_mfma_f32_16x16x32_bf16 v[106:109], v[156:159], v[196:199], v[106:109]
	v_mfma_f32_16x16x32_bf16 v[102:105], v[164:167], v[196:199], v[102:105]
	v_mfma_f32_16x16x32_bf16 v[90:93], v[156:159], v[204:207], v[90:93]
	v_mfma_f32_16x16x32_bf16 v[86:89], v[164:167], v[204:207], v[86:89]
	v_mfma_f32_16x16x32_bf16 v[74:77], v[156:159], v[212:215], v[74:77]
	v_mfma_f32_16x16x32_bf16 v[70:73], v[164:167], v[212:215], v[70:73]
	v_mfma_f32_16x16x32_bf16 v[122:125], v[160:163], v[192:195], v[122:125]
	v_mfma_f32_16x16x32_bf16 v[114:117], v[168:171], v[192:195], v[114:117]
	v_mfma_f32_16x16x32_bf16 v[106:109], v[160:163], v[200:203], v[106:109]
	v_mfma_f32_16x16x32_bf16 v[102:105], v[168:171], v[200:203], v[102:105]
	v_mfma_f32_16x16x32_bf16 v[90:93], v[160:163], v[208:211], v[90:93]
	v_mfma_f32_16x16x32_bf16 v[86:89], v[168:171], v[208:211], v[86:89]
	v_mfma_f32_16x16x32_bf16 v[74:77], v[160:163], v[216:219], v[74:77]
	v_mfma_f32_16x16x32_bf16 v[70:73], v[168:171], v[216:219], v[70:73]
	v_mfma_f32_16x16x32_bf16 v[126:129], v[172:175], v[188:191], v[126:129]
	v_mfma_f32_16x16x32_bf16 v[118:121], v[180:183], v[188:191], v[118:121]
	v_mfma_f32_16x16x32_bf16 v[110:113], v[172:175], v[196:199], v[110:113]
	v_mfma_f32_16x16x32_bf16 v[98:101], v[180:183], v[196:199], v[98:101]
	v_mfma_f32_16x16x32_bf16 v[94:97], v[172:175], v[204:207], v[94:97]
	v_mfma_f32_16x16x32_bf16 v[82:85], v[180:183], v[204:207], v[82:85]
	v_mfma_f32_16x16x32_bf16 v[78:81], v[172:175], v[212:215], v[78:81]
	v_mfma_f32_16x16x32_bf16 v[66:69], v[180:183], v[212:215], v[66:69]
	v_mfma_f32_16x16x32_bf16 v[126:129], v[176:179], v[192:195], v[126:129]
	v_mfma_f32_16x16x32_bf16 v[118:121], v[184:187], v[192:195], v[118:121]
	v_mfma_f32_16x16x32_bf16 v[110:113], v[176:179], v[200:203], v[110:113]
	v_mfma_f32_16x16x32_bf16 v[98:101], v[184:187], v[200:203], v[98:101]
	v_mfma_f32_16x16x32_bf16 v[94:97], v[176:179], v[208:211], v[94:97]
	v_mfma_f32_16x16x32_bf16 v[82:85], v[184:187], v[208:211], v[82:85]
	v_mfma_f32_16x16x32_bf16 v[78:81], v[176:179], v[216:219], v[78:81]
	v_mfma_f32_16x16x32_bf16 v[66:69], v[184:187], v[216:219], v[66:69]
	s_setprio 0
	s_barrier
	s_add_i32 s58, s47, s35
	v_lshl_add_u64 v[146:147], s[26:27], 0, v[134:135]
	s_mov_b32 m0, s58
	ds_read_b128 v[188:191], v151 offset:16384
	ds_read_b128 v[192:195], v151 offset:17408
	ds_read_b128 v[196:199], v151 offset:18432
	ds_read_b128 v[200:203], v151 offset:19456
	ds_read_b128 v[204:207], v151 offset:20480
	ds_read_b128 v[208:211], v151 offset:21504
	ds_read_b128 v[212:215], v151 offset:22528
	ds_read_b128 v[216:219], v151 offset:23552
	global_load_lds_dwordx4 v[146:147], off
	s_add_i32 m0, s58, 0x2000
	s_add_u32 s58, s26, 0x40000
	v_lshl_add_u64 v[220:221], s[26:27], 0, v[130:131]
	s_addc_u32 s59, s27, 0
	s_add_i32 s60, s48, s35
	global_load_lds_dwordx4 v[220:221], off
	v_lshl_add_u64 v[222:223], s[58:59], 0, v[134:135]
	s_mov_b32 m0, s60
	v_lshl_add_u64 v[224:225], s[28:29], 0, v[132:133]
	global_load_lds_dwordx4 v[222:223], off
	v_lshl_add_u64 v[222:223], s[58:59], 0, v[130:131]
	s_add_i32 m0, s60, 0x2000
	s_nop 0
	global_load_lds_dwordx4 v[222:223], off
	v_lshl_add_u64 v[222:223], s[28:29], 0, v[136:137]
	s_mov_b32 m0, s38
	s_nop 0
	global_load_lds_dwordx4 v[222:223], off
	s_mov_b32 m0, s39
	s_nop 0
	global_load_lds_dwordx4 v[224:225], off
	s_waitcnt vmcnt(8)
	s_waitcnt lgkmcnt(0)
	s_barrier
	s_setprio 1
	v_mfma_f32_16x16x32_bf16 v[58:61], v[156:159], v[188:191], v[58:61]
	v_mfma_f32_16x16x32_bf16 v[54:57], v[164:167], v[188:191], v[54:57]
	v_mfma_f32_16x16x32_bf16 v[42:45], v[156:159], v[196:199], v[42:45]
	v_mfma_f32_16x16x32_bf16 v[38:41], v[164:167], v[196:199], v[38:41]
	v_mfma_f32_16x16x32_bf16 v[26:29], v[156:159], v[204:207], v[26:29]
	v_mfma_f32_16x16x32_bf16 v[22:25], v[164:167], v[204:207], v[22:25]
	v_mfma_f32_16x16x32_bf16 v[14:17], v[156:159], v[212:215], v[14:17]
	v_mfma_f32_16x16x32_bf16 v[6:9], v[164:167], v[212:215], v[6:9]
	v_mfma_f32_16x16x32_bf16 v[58:61], v[160:163], v[192:195], v[58:61]
	v_mfma_f32_16x16x32_bf16 v[54:57], v[168:171], v[192:195], v[54:57]
	v_mfma_f32_16x16x32_bf16 v[42:45], v[160:163], v[200:203], v[42:45]
	v_mfma_f32_16x16x32_bf16 v[38:41], v[168:171], v[200:203], v[38:41]
	v_mfma_f32_16x16x32_bf16 v[26:29], v[160:163], v[208:211], v[26:29]
	v_mfma_f32_16x16x32_bf16 v[22:25], v[168:171], v[208:211], v[22:25]
	v_mfma_f32_16x16x32_bf16 v[14:17], v[160:163], v[216:219], v[14:17]
	v_mfma_f32_16x16x32_bf16 v[6:9], v[168:171], v[216:219], v[6:9]
	v_mfma_f32_16x16x32_bf16 v[62:65], v[172:175], v[188:191], v[62:65]
	v_mfma_f32_16x16x32_bf16 v[50:53], v[180:183], v[188:191], v[50:53]
	v_mfma_f32_16x16x32_bf16 v[46:49], v[172:175], v[196:199], v[46:49]
	v_mfma_f32_16x16x32_bf16 v[34:37], v[180:183], v[196:199], v[34:37]
	v_mfma_f32_16x16x32_bf16 v[30:33], v[172:175], v[204:207], v[30:33]
	v_mfma_f32_16x16x32_bf16 v[18:21], v[180:183], v[204:207], v[18:21]
	v_mfma_f32_16x16x32_bf16 v[10:13], v[172:175], v[212:215], v[10:13]
	v_mfma_f32_16x16x32_bf16 v[2:5], v[180:183], v[212:215], v[2:5]
	v_mfma_f32_16x16x32_bf16 v[62:65], v[176:179], v[192:195], v[62:65]
	v_mfma_f32_16x16x32_bf16 v[50:53], v[184:187], v[192:195], v[50:53]
	v_mfma_f32_16x16x32_bf16 v[46:49], v[176:179], v[200:203], v[46:49]
	v_mfma_f32_16x16x32_bf16 v[34:37], v[184:187], v[200:203], v[34:37]
	v_mfma_f32_16x16x32_bf16 v[30:33], v[176:179], v[208:211], v[30:33]
	v_mfma_f32_16x16x32_bf16 v[18:21], v[184:187], v[208:211], v[18:21]
	v_mfma_f32_16x16x32_bf16 v[10:13], v[176:179], v[216:219], v[10:13]
	v_mfma_f32_16x16x32_bf16 v[2:5], v[184:187], v[216:219], v[2:5]
	s_setprio 0
	s_barrier
	ds_read_b128 v[156:159], v154
	ds_read_b128 v[160:163], v154 offset:1024
	ds_read_b128 v[164:167], v154 offset:2048
	ds_read_b128 v[168:171], v154 offset:3072
	ds_read_b128 v[172:175], v155
	ds_read_b128 v[176:179], v155 offset:1024
	ds_read_b128 v[180:183], v155 offset:2048
	ds_read_b128 v[184:187], v155 offset:3072
	s_add_u32 s28, s28, 0x40000
	s_addc_u32 s29, s29, 0
	s_mov_b32 m0, s40
	v_lshl_add_u64 v[226:227], s[28:29], 0, v[136:137]
	ds_read_b128 v[188:191], v151 offset:32768
	ds_read_b128 v[192:195], v151 offset:33792
	ds_read_b128 v[196:199], v151 offset:34816
	ds_read_b128 v[200:203], v151 offset:35840
	ds_read_b128 v[204:207], v151 offset:36864
	ds_read_b128 v[208:211], v151 offset:37888
	ds_read_b128 v[212:215], v151 offset:38912
	ds_read_b128 v[216:219], v151 offset:39936
	global_load_lds_dwordx4 v[226:227], off
	v_lshl_add_u64 v[226:227], s[28:29], 0, v[132:133]
	s_mov_b32 m0, s41
	s_nop 0
	global_load_lds_dwordx4 v[226:227], off
	s_cmp_lg_u32 s57, 12
	s_cbranch_scc1 .Lss_pf_skip_a
	v_lshl_add_u32 v244, s6, 8, v1
	v_ashrrev_i32_e32 v245, 31, v244
	v_lshlrev_b64 v[244:245], 6, v[244:245]
	v_lshl_add_u64 v[244:245], s[8:9], 0, v[244:245]
	global_load_dwordx4 v[228:231], v[244:245], off
	global_load_dwordx4 v[232:235], v[244:245], off offset:16
	global_load_dwordx4 v[236:239], v[244:245], off offset:32
	global_load_dwordx4 v[240:243], v[244:245], off offset:48
.Lss_pf_skip_a:
	s_waitcnt vmcnt(8)
	s_waitcnt lgkmcnt(0)
	s_barrier
	s_setprio 1
	v_mfma_f32_16x16x32_bf16 v[122:125], v[156:159], v[188:191], v[122:125]
	v_mfma_f32_16x16x32_bf16 v[114:117], v[164:167], v[188:191], v[114:117]
	v_mfma_f32_16x16x32_bf16 v[106:109], v[156:159], v[196:199], v[106:109]
	v_mfma_f32_16x16x32_bf16 v[102:105], v[164:167], v[196:199], v[102:105]
	v_mfma_f32_16x16x32_bf16 v[90:93], v[156:159], v[204:207], v[90:93]
	v_mfma_f32_16x16x32_bf16 v[86:89], v[164:167], v[204:207], v[86:89]
	v_mfma_f32_16x16x32_bf16 v[74:77], v[156:159], v[212:215], v[74:77]
	v_mfma_f32_16x16x32_bf16 v[70:73], v[164:167], v[212:215], v[70:73]
	v_mfma_f32_16x16x32_bf16 v[122:125], v[160:163], v[192:195], v[122:125]
	v_mfma_f32_16x16x32_bf16 v[114:117], v[168:171], v[192:195], v[114:117]
	v_mfma_f32_16x16x32_bf16 v[106:109], v[160:163], v[200:203], v[106:109]
	v_mfma_f32_16x16x32_bf16 v[102:105], v[168:171], v[200:203], v[102:105]
	v_mfma_f32_16x16x32_bf16 v[90:93], v[160:163], v[208:211], v[90:93]
	v_mfma_f32_16x16x32_bf16 v[86:89], v[168:171], v[208:211], v[86:89]
	v_mfma_f32_16x16x32_bf16 v[74:77], v[160:163], v[216:219], v[74:77]
	v_mfma_f32_16x16x32_bf16 v[70:73], v[168:171], v[216:219], v[70:73]
	v_mfma_f32_16x16x32_bf16 v[126:129], v[172:175], v[188:191], v[126:129]
	v_mfma_f32_16x16x32_bf16 v[118:121], v[180:183], v[188:191], v[118:121]
	v_mfma_f32_16x16x32_bf16 v[110:113], v[172:175], v[196:199], v[110:113]
	v_mfma_f32_16x16x32_bf16 v[98:101], v[180:183], v[196:199], v[98:101]
	v_mfma_f32_16x16x32_bf16 v[94:97], v[172:175], v[204:207], v[94:97]
	v_mfma_f32_16x16x32_bf16 v[82:85], v[180:183], v[204:207], v[82:85]
	v_mfma_f32_16x16x32_bf16 v[78:81], v[172:175], v[212:215], v[78:81]
	v_mfma_f32_16x16x32_bf16 v[66:69], v[180:183], v[212:215], v[66:69]
	v_mfma_f32_16x16x32_bf16 v[126:129], v[176:179], v[192:195], v[126:129]
	v_mfma_f32_16x16x32_bf16 v[118:121], v[184:187], v[192:195], v[118:121]
	v_mfma_f32_16x16x32_bf16 v[110:113], v[176:179], v[200:203], v[110:113]
	v_mfma_f32_16x16x32_bf16 v[98:101], v[184:187], v[200:203], v[98:101]
	v_mfma_f32_16x16x32_bf16 v[94:97], v[176:179], v[208:211], v[94:97]
	v_mfma_f32_16x16x32_bf16 v[82:85], v[184:187], v[208:211], v[82:85]
	v_mfma_f32_16x16x32_bf16 v[78:81], v[176:179], v[216:219], v[78:81]
	v_mfma_f32_16x16x32_bf16 v[66:69], v[184:187], v[216:219], v[66:69]
	s_setprio 0
	s_barrier
	s_add_i32 s28, s51, s35
	v_lshl_add_u64 v[146:147], v[146:147], 0, s[12:13]
	s_mov_b32 m0, s28
	ds_read_b128 v[188:191], v151 offset:49152
	ds_read_b128 v[192:195], v151 offset:50176
	ds_read_b128 v[196:199], v151 offset:51200
	ds_read_b128 v[200:203], v151 offset:52224
	ds_read_b128 v[204:207], v151 offset:53248
	ds_read_b128 v[208:211], v151 offset:54272
	ds_read_b128 v[212:215], v151 offset:55296
	ds_read_b128 v[216:219], v151 offset:56320
	global_load_lds_dwordx4 v[146:147], off
	s_add_i32 m0, s28, 0x2000
	s_add_u32 s26, s26, 0x40080
	v_lshl_add_u64 v[146:147], v[220:221], 0, s[12:13]
	s_addc_u32 s27, s27, 0
	s_add_i32 s28, s52, s35
	global_load_lds_dwordx4 v[146:147], off
	v_lshl_add_u64 v[146:147], s[26:27], 0, v[134:135]
	s_mov_b32 m0, s28
	s_nop 0
	global_load_lds_dwordx4 v[146:147], off
	v_lshl_add_u64 v[146:147], s[26:27], 0, v[130:131]
	s_add_i32 m0, s28, 0x2000
	s_nop 0
	global_load_lds_dwordx4 v[146:147], off
	v_lshl_add_u64 v[146:147], v[222:223], 0, s[12:13]
	s_mov_b32 m0, s44
	s_nop 0
	global_load_lds_dwordx4 v[146:147], off
	v_lshl_add_u64 v[146:147], v[224:225], 0, s[12:13]
	s_mov_b32 m0, s45
	s_nop 0
	global_load_lds_dwordx4 v[146:147], off
	s_waitcnt vmcnt(8)
	s_waitcnt lgkmcnt(0)
	s_barrier
	s_setprio 1
	v_mfma_f32_16x16x32_bf16 v[58:61], v[156:159], v[188:191], v[58:61]
	v_mfma_f32_16x16x32_bf16 v[54:57], v[164:167], v[188:191], v[54:57]
	v_mfma_f32_16x16x32_bf16 v[42:45], v[156:159], v[196:199], v[42:45]
	v_mfma_f32_16x16x32_bf16 v[38:41], v[164:167], v[196:199], v[38:41]
	v_mfma_f32_16x16x32_bf16 v[26:29], v[156:159], v[204:207], v[26:29]
	v_mfma_f32_16x16x32_bf16 v[22:25], v[164:167], v[204:207], v[22:25]
	v_mfma_f32_16x16x32_bf16 v[14:17], v[156:159], v[212:215], v[14:17]
	v_mfma_f32_16x16x32_bf16 v[6:9], v[164:167], v[212:215], v[6:9]
	v_mfma_f32_16x16x32_bf16 v[58:61], v[160:163], v[192:195], v[58:61]
	v_mfma_f32_16x16x32_bf16 v[54:57], v[168:171], v[192:195], v[54:57]
	v_mfma_f32_16x16x32_bf16 v[42:45], v[160:163], v[200:203], v[42:45]
	v_mfma_f32_16x16x32_bf16 v[38:41], v[168:171], v[200:203], v[38:41]
	v_mfma_f32_16x16x32_bf16 v[26:29], v[160:163], v[208:211], v[26:29]
	v_mfma_f32_16x16x32_bf16 v[22:25], v[168:171], v[208:211], v[22:25]
	v_mfma_f32_16x16x32_bf16 v[14:17], v[160:163], v[216:219], v[14:17]
	v_mfma_f32_16x16x32_bf16 v[6:9], v[168:171], v[216:219], v[6:9]
	v_mfma_f32_16x16x32_bf16 v[62:65], v[172:175], v[188:191], v[62:65]
	v_mfma_f32_16x16x32_bf16 v[50:53], v[180:183], v[188:191], v[50:53]
	v_mfma_f32_16x16x32_bf16 v[46:49], v[172:175], v[196:199], v[46:49]
	v_mfma_f32_16x16x32_bf16 v[34:37], v[180:183], v[196:199], v[34:37]
	v_mfma_f32_16x16x32_bf16 v[30:33], v[172:175], v[204:207], v[30:33]
	v_mfma_f32_16x16x32_bf16 v[18:21], v[180:183], v[204:207], v[18:21]
	v_mfma_f32_16x16x32_bf16 v[10:13], v[172:175], v[212:215], v[10:13]
	v_mfma_f32_16x16x32_bf16 v[2:5], v[180:183], v[212:215], v[2:5]
	v_mfma_f32_16x16x32_bf16 v[62:65], v[176:179], v[192:195], v[62:65]
	v_mfma_f32_16x16x32_bf16 v[50:53], v[184:187], v[192:195], v[50:53]
	v_mfma_f32_16x16x32_bf16 v[46:49], v[176:179], v[200:203], v[46:49]
	v_mfma_f32_16x16x32_bf16 v[34:37], v[184:187], v[200:203], v[34:37]
	v_mfma_f32_16x16x32_bf16 v[30:33], v[176:179], v[208:211], v[30:33]
	v_mfma_f32_16x16x32_bf16 v[18:21], v[184:187], v[208:211], v[18:21]
	v_mfma_f32_16x16x32_bf16 v[10:13], v[176:179], v[216:219], v[10:13]
	v_mfma_f32_16x16x32_bf16 v[2:5], v[184:187], v[216:219], v[2:5]
	s_setprio 0
	s_barrier
	s_add_i32 s57, s57, 2
	s_add_u32 s24, s24, 0x100
	s_addc_u32 s25, s25, 0
	s_add_u32 s55, s55, 0x100
	s_addc_u32 s56, s56, 0
	s_cmp_gt_u32 s57, 13
	s_cbranch_scc0 .LBB0_252
	s_and_b64 vcc, exec, s[14:15]
	s_cbranch_vccz .LBB0_255
	s_barrier

.LBB0_2429:
	ds_read_b128 v[156:159], v149
	ds_read_b128 v[160:163], v149 offset:1024
	ds_read_b128 v[164:167], v149 offset:2048
	ds_read_b128 v[168:171], v149 offset:3072
	ds_read_b128 v[172:175], v150
	ds_read_b128 v[176:179], v150 offset:1024
	ds_read_b128 v[180:183], v150 offset:2048
	ds_read_b128 v[184:187], v150 offset:3072
	s_add_u32 s26, s24, 0xfffc0080
	s_addc_u32 s27, s25, -1
	s_cmp_eq_u32 s57, 12
	s_cselect_b32 s29, s19, s27
	s_cselect_b32 s28, s53, s26
	s_cselect_b32 s27, s17, s56
	s_cselect_b32 s26, s54, s55
	v_lshl_add_u64 v[146:147], s[24:25], 0, v[138:139]
	s_add_i32 m0, s38, 0xc000
	ds_read_b128 v[188:191], v151
	ds_read_b128 v[192:195], v151 offset:1024
	ds_read_b128 v[196:199], v151 offset:2048
	ds_read_b128 v[200:203], v151 offset:3072
	ds_read_b128 v[204:207], v151 offset:4096
	ds_read_b128 v[208:211], v151 offset:5120
	ds_read_b128 v[212:215], v151 offset:6144
	ds_read_b128 v[216:219], v151 offset:7168
	global_load_lds_dwordx4 v[146:147], off
	v_lshl_add_u64 v[146:147], s[24:25], 0, v[140:141]
	s_add_i32 m0, s38, 0xe000
	s_nop 0
	global_load_lds_dwordx4 v[146:147], off
	s_waitcnt vmcnt(8)
	s_waitcnt lgkmcnt(0)
	s_barrier
	s_setprio 1
	v_mfma_f32_16x16x32_bf16 v[122:125], v[156:159], v[188:191], v[122:125]
	v_mfma_f32_16x16x32_bf16 v[114:117], v[164:167], v[188:191], v[114:117]
	v_mfma_f32_16x16x32_bf16 v[106:109], v[156:159], v[196:199], v[106:109]
	v_mfma_f32_16x16x32_bf16 v[102:105], v[164:167], v[196:199], v[102:105]
	v_mfma_f32_16x16x32_bf16 v[90:93], v[156:159], v[204:207], v[90:93]
	v_mfma_f32_16x16x32_bf16 v[86:89], v[164:167], v[204:207], v[86:89]
	v_mfma_f32_16x16x32_bf16 v[74:77], v[156:159], v[212:215], v[74:77]
	v_mfma_f32_16x16x32_bf16 v[70:73], v[164:167], v[212:215], v[70:73]
	v_mfma_f32_16x16x32_bf16 v[122:125], v[160:163], v[192:195], v[122:125]
	v_mfma_f32_16x16x32_bf16 v[114:117], v[168:171], v[192:195], v[114:117]
	v_mfma_f32_16x16x32_bf16 v[106:109], v[160:163], v[200:203], v[106:109]
	v_mfma_f32_16x16x32_bf16 v[102:105], v[168:171], v[200:203], v[102:105]
	v_mfma_f32_16x16x32_bf16 v[90:93], v[160:163], v[208:211], v[90:93]
	v_mfma_f32_16x16x32_bf16 v[86:89], v[168:171], v[208:211], v[86:89]
	v_mfma_f32_16x16x32_bf16 v[74:77], v[160:163], v[216:219], v[74:77]
	v_mfma_f32_16x16x32_bf16 v[70:73], v[168:171], v[216:219], v[70:73]
	v_mfma_f32_16x16x32_bf16 v[126:129], v[172:175], v[188:191], v[126:129]
	v_mfma_f32_16x16x32_bf16 v[118:121], v[180:183], v[188:191], v[118:121]
	v_mfma_f32_16x16x32_bf16 v[110:113], v[172:175], v[196:199], v[110:113]
	v_mfma_f32_16x16x32_bf16 v[98:101], v[180:183], v[196:199], v[98:101]
	v_mfma_f32_16x16x32_bf16 v[94:97], v[172:175], v[204:207], v[94:97]
	v_mfma_f32_16x16x32_bf16 v[82:85], v[180:183], v[204:207], v[82:85]
	v_mfma_f32_16x16x32_bf16 v[78:81], v[172:175], v[212:215], v[78:81]
	v_mfma_f32_16x16x32_bf16 v[66:69], v[180:183], v[212:215], v[66:69]
	v_mfma_f32_16x16x32_bf16 v[126:129], v[176:179], v[192:195], v[126:129]
	v_mfma_f32_16x16x32_bf16 v[118:121], v[184:187], v[192:195], v[118:121]
	v_mfma_f32_16x16x32_bf16 v[110:113], v[176:179], v[200:203], v[110:113]
	v_mfma_f32_16x16x32_bf16 v[98:101], v[184:187], v[200:203], v[98:101]
	v_mfma_f32_16x16x32_bf16 v[94:97], v[176:179], v[208:211], v[94:97]
	v_mfma_f32_16x16x32_bf16 v[82:85], v[184:187], v[208:211], v[82:85]
	v_mfma_f32_16x16x32_bf16 v[78:81], v[176:179], v[216:219], v[78:81]
	v_mfma_f32_16x16x32_bf16 v[66:69], v[184:187], v[216:219], v[66:69]
	s_setprio 0
	s_barrier
	s_add_i32 s58, s47, s35
	v_lshl_add_u64 v[146:147], s[26:27], 0, v[134:135]
	s_mov_b32 m0, s58
	ds_read_b128 v[188:191], v151 offset:16384
	ds_read_b128 v[192:195], v151 offset:17408
	ds_read_b128 v[196:199], v151 offset:18432
	ds_read_b128 v[200:203], v151 offset:19456
	ds_read_b128 v[204:207], v151 offset:20480
	ds_read_b128 v[208:211], v151 offset:21504
	ds_read_b128 v[212:215], v151 offset:22528
	ds_read_b128 v[216:219], v151 offset:23552
	global_load_lds_dwordx4 v[146:147], off
	s_add_i32 m0, s58, 0x2000
	s_add_u32 s58, s26, 0x40000
	v_lshl_add_u64 v[220:221], s[26:27], 0, v[130:131]
	s_addc_u32 s59, s27, 0
	s_add_i32 s60, s48, s35
	global_load_lds_dwordx4 v[220:221], off
	v_lshl_add_u64 v[222:223], s[58:59], 0, v[134:135]
	s_mov_b32 m0, s60
	v_lshl_add_u64 v[224:225], s[28:29], 0, v[132:133]
	global_load_lds_dwordx4 v[222:223], off
	v_lshl_add_u64 v[222:223], s[58:59], 0, v[130:131]
	s_add_i32 m0, s60, 0x2000
	s_nop 0
	global_load_lds_dwordx4 v[222:223], off
	v_lshl_add_u64 v[222:223], s[28:29], 0, v[136:137]
	s_mov_b32 m0, s38
	s_nop 0
	global_load_lds_dwordx4 v[222:223], off
	s_mov_b32 m0, s39
	s_nop 0
	global_load_lds_dwordx4 v[224:225], off
	s_waitcnt vmcnt(8)
	s_waitcnt lgkmcnt(0)
	s_barrier
	s_setprio 1
	v_mfma_f32_16x16x32_bf16 v[58:61], v[156:159], v[188:191], v[58:61]
	v_mfma_f32_16x16x32_bf16 v[54:57], v[164:167], v[188:191], v[54:57]
	v_mfma_f32_16x16x32_bf16 v[42:45], v[156:159], v[196:199], v[42:45]
	v_mfma_f32_16x16x32_bf16 v[38:41], v[164:167], v[196:199], v[38:41]
	v_mfma_f32_16x16x32_bf16 v[26:29], v[156:159], v[204:207], v[26:29]
	v_mfma_f32_16x16x32_bf16 v[22:25], v[164:167], v[204:207], v[22:25]
	v_mfma_f32_16x16x32_bf16 v[14:17], v[156:159], v[212:215], v[14:17]
	v_mfma_f32_16x16x32_bf16 v[6:9], v[164:167], v[212:215], v[6:9]
	v_mfma_f32_16x16x32_bf16 v[58:61], v[160:163], v[192:195], v[58:61]
	v_mfma_f32_16x16x32_bf16 v[54:57], v[168:171], v[192:195], v[54:57]
	v_mfma_f32_16x16x32_bf16 v[42:45], v[160:163], v[200:203], v[42:45]
	v_mfma_f32_16x16x32_bf16 v[38:41], v[168:171], v[200:203], v[38:41]
	v_mfma_f32_16x16x32_bf16 v[26:29], v[160:163], v[208:211], v[26:29]
	v_mfma_f32_16x16x32_bf16 v[22:25], v[168:171], v[208:211], v[22:25]
	v_mfma_f32_16x16x32_bf16 v[14:17], v[160:163], v[216:219], v[14:17]
	v_mfma_f32_16x16x32_bf16 v[6:9], v[168:171], v[216:219], v[6:9]
	v_mfma_f32_16x16x32_bf16 v[62:65], v[172:175], v[188:191], v[62:65]
	v_mfma_f32_16x16x32_bf16 v[50:53], v[180:183], v[188:191], v[50:53]
	v_mfma_f32_16x16x32_bf16 v[46:49], v[172:175], v[196:199], v[46:49]
	v_mfma_f32_16x16x32_bf16 v[34:37], v[180:183], v[196:199], v[34:37]
	v_mfma_f32_16x16x32_bf16 v[30:33], v[172:175], v[204:207], v[30:33]
	v_mfma_f32_16x16x32_bf16 v[18:21], v[180:183], v[204:207], v[18:21]
	v_mfma_f32_16x16x32_bf16 v[10:13], v[172:175], v[212:215], v[10:13]
	v_mfma_f32_16x16x32_bf16 v[2:5], v[180:183], v[212:215], v[2:5]
	v_mfma_f32_16x16x32_bf16 v[62:65], v[176:179], v[192:195], v[62:65]
	v_mfma_f32_16x16x32_bf16 v[50:53], v[184:187], v[192:195], v[50:53]
	v_mfma_f32_16x16x32_bf16 v[46:49], v[176:179], v[200:203], v[46:49]
	v_mfma_f32_16x16x32_bf16 v[34:37], v[184:187], v[200:203], v[34:37]
	v_mfma_f32_16x16x32_bf16 v[30:33], v[176:179], v[208:211], v[30:33]
	v_mfma_f32_16x16x32_bf16 v[18:21], v[184:187], v[208:211], v[18:21]
	v_mfma_f32_16x16x32_bf16 v[10:13], v[176:179], v[216:219], v[10:13]
	v_mfma_f32_16x16x32_bf16 v[2:5], v[184:187], v[216:219], v[2:5]
	s_setprio 0
	s_barrier
	ds_read_b128 v[156:159], v154
	ds_read_b128 v[160:163], v154 offset:1024
	ds_read_b128 v[164:167], v154 offset:2048
	ds_read_b128 v[168:171], v154 offset:3072
	ds_read_b128 v[172:175], v155
	ds_read_b128 v[176:179], v155 offset:1024
	ds_read_b128 v[180:183], v155 offset:2048
	ds_read_b128 v[184:187], v155 offset:3072
	s_add_u32 s28, s28, 0x40000
	s_addc_u32 s29, s29, 0
	s_mov_b32 m0, s40
	v_lshl_add_u64 v[226:227], s[28:29], 0, v[136:137]
	ds_read_b128 v[188:191], v151 offset:32768
	ds_read_b128 v[192:195], v151 offset:33792
	ds_read_b128 v[196:199], v151 offset:34816
	ds_read_b128 v[200:203], v151 offset:35840
	ds_read_b128 v[204:207], v151 offset:36864
	ds_read_b128 v[208:211], v151 offset:37888
	ds_read_b128 v[212:215], v151 offset:38912
	ds_read_b128 v[216:219], v151 offset:39936
	global_load_lds_dwordx4 v[226:227], off
	v_lshl_add_u64 v[226:227], s[28:29], 0, v[132:133]
	s_mov_b32 m0, s41
	s_nop 0
	global_load_lds_dwordx4 v[226:227], off
	s_cmp_lg_u32 s57, 12
	s_cbranch_scc1 .Lss_pf_skip_b
	v_lshl_add_u32 v244, s6, 8, v1
	v_ashrrev_i32_e32 v245, 31, v244
	v_lshlrev_b64 v[244:245], 6, v[244:245]
	v_lshl_add_u64 v[244:245], s[10:11], 0, v[244:245]
	global_load_dwordx4 v[228:231], v[244:245], off
	global_load_dwordx4 v[232:235], v[244:245], off offset:16
	global_load_dwordx4 v[236:239], v[244:245], off offset:32
	global_load_dwordx4 v[240:243], v[244:245], off offset:48
